# attention V-phase: bf16 packs spread over both exp loops (one S0 pack per two exps in the first loop, S1 packs lagging in the second)
# baseline (speedup 1.0000x reference)
; __device__ __forceinline__ void expHalf(f32x16& p0) {
; #pragma unroll
;     for (int r = 0; r < 16; ++r) p0[r] = __builtin_amdgcn_exp2f(p0[r]);
; }
; __device__ __forceinline__ void finishSM(f32x16& p0, f32x16& p1, float& l_reg, bf16x8& pa0, bf16x8& pa1, bf16x8& pa2, bf16x8& pa3) {
;     float ps = 0;
; #pragma unroll
;     for (int r = 0; r < 16; ++r) ps += p0[r];
; #pragma unroll
;     for (int r = 0; r < 16; ++r) ps += p1[r];
;     l_reg += ps;
;     ...
;     PK4(p0, 0, pa0); PK4(p0, 8, pa1); PK4(p1, 0, pa2); PK4(p1, 8, pa3);
.Lat_far_g0l:
	v_exp_f32_e32 v112, v112
	v_exp_f32_e32 v113, v113
	v_exp_f32_e32 v114, v114
	v_add_f32_e32 v64, v64, v112
	v_exp_f32_e32 v115, v115
	v_add_f32_e32 v65, v65, v113
	v_exp_f32_e32 v116, v116
	v_add_f32_e32 v66, v66, v114
	v_cvt_pk_bf16_f32 v208, v112, v113
	v_exp_f32_e32 v117, v117
	v_add_f32_e32 v67, v67, v115
	v_exp_f32_e32 v118, v118
	v_add_f32_e32 v64, v64, v116
	v_cvt_pk_bf16_f32 v209, v114, v115
	v_exp_f32_e32 v119, v119
	v_add_f32_e32 v65, v65, v117
	v_exp_f32_e32 v120, v120
	v_add_f32_e32 v66, v66, v118
	v_cvt_pk_bf16_f32 v210, v116, v117
	v_exp_f32_e32 v121, v121
	v_add_f32_e32 v67, v67, v119
	v_exp_f32_e32 v122, v122
	v_add_f32_e32 v64, v64, v120
	v_cvt_pk_bf16_f32 v211, v118, v119
	v_exp_f32_e32 v123, v123
	v_add_f32_e32 v65, v65, v121
	v_exp_f32_e32 v124, v124
	v_add_f32_e32 v66, v66, v122
	v_cvt_pk_bf16_f32 v212, v120, v121
	v_exp_f32_e32 v125, v125
	v_add_f32_e32 v67, v67, v123
	v_exp_f32_e32 v126, v126
	v_add_f32_e32 v64, v64, v124
	v_cvt_pk_bf16_f32 v213, v122, v123
	v_exp_f32_e32 v127, v127
	v_add_f32_e32 v65, v65, v125
	v_exp_f32_e32 v192, v192
	v_add_f32_e32 v66, v66, v126
	v_cvt_pk_bf16_f32 v214, v124, v125
	v_exp_f32_e32 v193, v193
	v_add_f32_e32 v67, v67, v127
	v_cvt_pk_bf16_f32 v215, v126, v127
	v_exp_f32_e32 v194, v194
	v_add_f32_e32 v64, v64, v192
	v_exp_f32_e32 v195, v195
	v_add_f32_e32 v65, v65, v193
	v_cvt_pk_bf16_f32 v216, v192, v193
	v_exp_f32_e32 v196, v196
	v_add_f32_e32 v66, v66, v194
	v_exp_f32_e32 v197, v197
	v_add_f32_e32 v67, v67, v195
	v_cvt_pk_bf16_f32 v217, v194, v195
	v_exp_f32_e32 v198, v198
	v_add_f32_e32 v64, v64, v196
	v_exp_f32_e32 v199, v199
	v_add_f32_e32 v65, v65, v197
	v_cvt_pk_bf16_f32 v218, v196, v197
	v_exp_f32_e32 v200, v200
	v_add_f32_e32 v66, v66, v198
	v_exp_f32_e32 v201, v201
	v_add_f32_e32 v67, v67, v199
	v_cvt_pk_bf16_f32 v219, v198, v199
	v_exp_f32_e32 v202, v202
	v_add_f32_e32 v64, v64, v200
	v_exp_f32_e32 v203, v203
	v_add_f32_e32 v65, v65, v201
	v_cvt_pk_bf16_f32 v220, v200, v201
	v_exp_f32_e32 v204, v204
	v_add_f32_e32 v66, v66, v202
	v_exp_f32_e32 v205, v205
	v_add_f32_e32 v67, v67, v203
	v_cvt_pk_bf16_f32 v221, v202, v203
	v_exp_f32_e32 v206, v206
	v_add_f32_e32 v64, v64, v204
	v_exp_f32_e32 v207, v207
	v_add_f32_e32 v65, v65, v205
	v_cvt_pk_bf16_f32 v222, v204, v205
	v_add_f32_e32 v66, v66, v206
	v_add_f32_e32 v67, v67, v207
	v_cvt_pk_bf16_f32 v223, v206, v207
	s_add_i32 s99, s23, 64
	s_cmp_ge_i32 s99, s30
	s_cselect_b32 s6, s22, s98
	s_cmp_le_i32 s99, s29
	s_cselect_b32 s6, s21, s6
	s_nop 0
	s_cmp_lg_u32 s6, s9
	s_cbranch_scc0 .Lat_c0same_g0l
	s_mov_b32 s9, s6
	v_mov_b32_e32 v68, s9
	v_mov_b32_e32 v69, s9
	v_mov_b32_e32 v70, s9
	v_mov_b32_e32 v71, s9
	v_mov_b32_e32 v72, s9
	v_mov_b32_e32 v73, s9
	v_mov_b32_e32 v74, s9
	v_mov_b32_e32 v75, s9
	v_mov_b32_e32 v76, s9
	v_mov_b32_e32 v77, s9
	v_mov_b32_e32 v78, s9
	v_mov_b32_e32 v79, s9
	v_mov_b32_e32 v80, s9
	v_mov_b32_e32 v81, s9
	v_mov_b32_e32 v82, s9
	v_mov_b32_e32 v83, s9

; #define SBAR() __builtin_amdgcn_sched_barrier(0)
; #define PVLOAD(D0, X) do { X[0] = tr_read<v_rd_off(D0, 0, 0)>(vb); X[1] = tr_read<v_rd_off(D0, 0, 1)>(vb); X[2] = tr_read<v_rd_off(D0, 1, 0)>(vb); X[3] = tr_read<v_rd_off(D0, 1, 1)>(vb); \
;     X[4] = tr_read<v_rd_off(D0, 2, 0)>(vb); X[5] = tr_read<v_rd_off(D0, 2, 1)>(vb); X[6] = tr_read<v_rd_off(D0, 3, 0)>(vb); X[7] = tr_read<v_rd_off(D0, 3, 1)>(vb); } while (0)
; #define PVMMA(OD, X) do { OD = __builtin_amdgcn_mfma_f32_32x32x16_bf16(pa0, PVPK(X[0], X[1]), OD, 0, 0, 0); OD = __builtin_amdgcn_mfma_f32_32x32x16_bf16(pa1, PVPK(X[2], X[3]), OD, 0, 0, 0); \
;     OD = __builtin_amdgcn_mfma_f32_32x32x16_bf16(pa2, PVPK(X[4], X[5]), OD, 0, 0, 0); OD = __builtin_amdgcn_mfma_f32_32x32x16_bf16(pa3, PVPK(X[6], X[7]), OD, 0, 0, 0); } while (0)
; #define PVWAIT() do { asm volatile("s_waitcnt lgkmcnt(0)" ::: "memory"); SBAR(); } while (0)
; #define PVEXP(P, B, N) do { _Pragma("unroll") for (int r = (B); r < (B) + (N); ++r) P[r] = __builtin_amdgcn_exp2f(P[r]); } while (0)
; __device__ __forceinline__ void expHalf(f32x16& p0) {
; #pragma unroll
;     for (int r = 0; r < 16; ++r) p0[r] = __builtin_amdgcn_exp2f(p0[r]);
; }
; __device__ __forceinline__ void finishSM(f32x16& p0, f32x16& p1, float& l_reg, bf16x8& pa0, bf16x8& pa1, bf16x8& pa2, bf16x8& pa3) {
;     float ps = 0;
; #pragma unroll
;     for (int r = 0; r < 16; ++r) ps += p0[r];
; #pragma unroll
;     for (int r = 0; r < 16; ++r) ps += p1[r];
;     l_reg += ps;
;     ...
;     PK4(p0, 0, pa0); PK4(p0, 8, pa1); PK4(p1, 0, pa2); PK4(p1, 8, pa3);
; template <int NB> __device__ __forceinline__ void pv_blocks(f32x16* o, int vb, bf16x8 pa0, bf16x8 pa1, bf16x8 pa2, bf16x8 pa3, f32x16& pe0, f32x16& pe1) {
;     s16x4 x[8], y[8];
;     ...
;     PVLOAD(0, x); PVWAIT();
;     if (NB == 4) {
;         PVLOAD(1, y); SBAR(); PVMMA(o[0], x); PVEXP(pe0, 0, 8); SBAR(); PVWAIT();
;         PVLOAD(2, x); SBAR(); PVMMA(o[1], y); PVEXP(pe0, 8, 8); SBAR(); PVWAIT();
;         PVLOAD(3, y); SBAR(); PVMMA(o[2], x); PVEXP(pe1, 0, 8); SBAR(); PVWAIT();
;         PVMMA(o[3], y); PVEXP(pe1, 8, 8);
;     } else {
;         PVLOAD(1, y); SBAR(); PVMMA(o[0], x); PVEXP(pe0, 0, 16); SBAR(); PVWAIT();
;         PVMMA(o[1], y); PVEXP(pe1, 0, 16);
;     }
.Lat_far_g0p:
	v_exp_f32_e32 v112, v112
	v_exp_f32_e32 v113, v113
	v_exp_f32_e32 v114, v114
	v_add_f32_e32 v64, v64, v112
	v_exp_f32_e32 v115, v115
	v_add_f32_e32 v65, v65, v113
	v_exp_f32_e32 v116, v116
	v_add_f32_e32 v66, v66, v114
	v_cvt_pk_bf16_f32 v208, v112, v113
	v_exp_f32_e32 v117, v117
	v_add_f32_e32 v67, v67, v115
	v_exp_f32_e32 v118, v118
	v_add_f32_e32 v64, v64, v116
	v_cvt_pk_bf16_f32 v209, v114, v115
	v_exp_f32_e32 v119, v119
	v_add_f32_e32 v65, v65, v117
	v_exp_f32_e32 v120, v120
	v_add_f32_e32 v66, v66, v118
	v_cvt_pk_bf16_f32 v210, v116, v117
	v_exp_f32_e32 v121, v121
	v_add_f32_e32 v67, v67, v119
	v_exp_f32_e32 v122, v122
	v_add_f32_e32 v64, v64, v120
	v_cvt_pk_bf16_f32 v211, v118, v119
	v_exp_f32_e32 v123, v123
	v_add_f32_e32 v65, v65, v121
	v_exp_f32_e32 v124, v124
	v_add_f32_e32 v66, v66, v122
	v_cvt_pk_bf16_f32 v212, v120, v121
	v_exp_f32_e32 v125, v125
	v_add_f32_e32 v67, v67, v123
	v_exp_f32_e32 v126, v126
	v_add_f32_e32 v64, v64, v124
	v_cvt_pk_bf16_f32 v213, v122, v123
	v_exp_f32_e32 v127, v127
	v_add_f32_e32 v65, v65, v125
	v_exp_f32_e32 v192, v192
	v_add_f32_e32 v66, v66, v126
	v_cvt_pk_bf16_f32 v214, v124, v125
	v_exp_f32_e32 v193, v193
	v_add_f32_e32 v67, v67, v127
	v_cvt_pk_bf16_f32 v215, v126, v127
	v_exp_f32_e32 v194, v194
	v_add_f32_e32 v64, v64, v192
	v_exp_f32_e32 v195, v195
	v_add_f32_e32 v65, v65, v193
	v_cvt_pk_bf16_f32 v216, v192, v193
	v_exp_f32_e32 v196, v196
	v_add_f32_e32 v66, v66, v194
	v_exp_f32_e32 v197, v197
	v_add_f32_e32 v67, v67, v195
	v_cvt_pk_bf16_f32 v217, v194, v195
	v_exp_f32_e32 v198, v198
	v_add_f32_e32 v64, v64, v196
	v_exp_f32_e32 v199, v199
	v_add_f32_e32 v65, v65, v197
	v_cvt_pk_bf16_f32 v218, v196, v197
	v_exp_f32_e32 v200, v200
	v_add_f32_e32 v66, v66, v198
	v_exp_f32_e32 v201, v201
	v_add_f32_e32 v67, v67, v199
	v_cvt_pk_bf16_f32 v219, v198, v199
	v_exp_f32_e32 v202, v202
	v_add_f32_e32 v64, v64, v200
	v_exp_f32_e32 v203, v203
	v_add_f32_e32 v65, v65, v201
	v_cvt_pk_bf16_f32 v220, v200, v201
	v_exp_f32_e32 v204, v204
	v_add_f32_e32 v66, v66, v202
	v_exp_f32_e32 v205, v205
	v_add_f32_e32 v67, v67, v203
	v_cvt_pk_bf16_f32 v221, v202, v203
	v_exp_f32_e32 v206, v206
	v_add_f32_e32 v64, v64, v204
	v_exp_f32_e32 v207, v207
	v_add_f32_e32 v65, v65, v205
	v_cvt_pk_bf16_f32 v222, v204, v205
	v_add_f32_e32 v66, v66, v206
	v_add_f32_e32 v67, v67, v207
	v_cvt_pk_bf16_f32 v223, v206, v207
	s_nop 1
	s_waitcnt vmcnt(0)
	s_barrier
	s_setprio 0
	ds_read_b64_tr_b16 v[84:85], v168 offset:0
	ds_read_b64_tr_b16 v[86:87], v168 offset:2048
	ds_read_b64_tr_b16 v[88:89], v168 offset:4096
	ds_read_b64_tr_b16 v[90:91], v168 offset:6144
	ds_read_b64_tr_b16 v[92:93], v168 offset:8192
	ds_read_b64_tr_b16 v[94:95], v168 offset:10240
	ds_read_b64_tr_b16 v[128:129], v168 offset:12288
	ds_read_b64_tr_b16 v[130:131], v168 offset:14336
	ds_read_b64_tr_b16 v[132:133], v168 offset:512
	ds_read_b64_tr_b16 v[134:135], v168 offset:2560
	ds_read_b64_tr_b16 v[140:141], v168 offset:4608
	ds_read_b64_tr_b16 v[142:143], v168 offset:6656
	ds_read_b64_tr_b16 v[152:153], v168 offset:8704
	ds_read_b64_tr_b16 v[154:155], v168 offset:10752
	s_waitcnt lgkmcnt(12)
	v_mfma_f32_32x32x16_bf16 v[0:15], v[208:211], v[84:87], v[0:15]
	ds_read_b64_tr_b16 v[160:161], v168 offset:12800
	ds_read_b64_tr_b16 v[162:163], v168 offset:14848
	s_waitcnt lgkmcnt(12)
	v_mfma_f32_32x32x16_bf16 v[0:15], v[212:215], v[88:91], v[0:15]
	ds_read_b64_tr_b16 v[84:85], v168 offset:1024
	ds_read_b64_tr_b16 v[86:87], v168 offset:3072
	s_waitcnt lgkmcnt(12)
	v_mfma_f32_32x32x16_bf16 v[0:15], v[216:219], v[92:95], v[0:15]
	ds_read_b64_tr_b16 v[88:89], v168 offset:5120
	ds_read_b64_tr_b16 v[90:91], v168 offset:7168
	s_waitcnt lgkmcnt(12)
	v_mfma_f32_32x32x16_bf16 v[0:15], v[220:223], v[128:131], v[0:15]
	ds_read_b64_tr_b16 v[92:93], v168 offset:9216
	ds_read_b64_tr_b16 v[94:95], v168 offset:11264
	s_waitcnt lgkmcnt(12)
	v_mfma_f32_32x32x16_bf16 v[16:31], v[208:211], v[132:135], v[16:31]
	ds_read_b64_tr_b16 v[128:129], v168 offset:13312
	ds_read_b64_tr_b16 v[130:131], v168 offset:15360
	s_waitcnt lgkmcnt(12)
	v_mfma_f32_32x32x16_bf16 v[16:31], v[212:215], v[140:143], v[16:31]
	ds_read_b64_tr_b16 v[132:133], v168 offset:1536
	ds_read_b64_tr_b16 v[134:135], v168 offset:3584
	s_waitcnt lgkmcnt(12)
	v_mfma_f32_32x32x16_bf16 v[16:31], v[216:219], v[152:155], v[16:31]
	ds_read_b64_tr_b16 v[140:141], v168 offset:5632
	ds_read_b64_tr_b16 v[142:143], v168 offset:7680
	s_waitcnt lgkmcnt(12)
	v_mfma_f32_32x32x16_bf16 v[16:31], v[220:223], v[160:163], v[16:31]
	ds_read_b64_tr_b16 v[152:153], v168 offset:9728
	ds_read_b64_tr_b16 v[154:155], v168 offset:11776
	s_waitcnt lgkmcnt(12)
	v_mfma_f32_32x32x16_bf16 v[32:47], v[208:211], v[84:87], v[32:47]
	ds_read_b64_tr_b16 v[160:161], v168 offset:13824
	ds_read_b64_tr_b16 v[162:163], v168 offset:15872
	v_xor_b32_e32 v168, 0x4000, v168
	s_waitcnt lgkmcnt(12)
	v_mfma_f32_32x32x16_bf16 v[32:47], v[212:215], v[88:91], v[32:47]
	s_waitcnt lgkmcnt(10)
	v_mfma_f32_32x32x16_bf16 v[32:47], v[216:219], v[92:95], v[32:47]
	s_waitcnt lgkmcnt(8)
	v_mfma_f32_32x32x16_bf16 v[32:47], v[220:223], v[128:131], v[32:47]
	s_waitcnt lgkmcnt(6)
	v_mfma_f32_32x32x16_bf16 v[48:63], v[208:211], v[132:135], v[48:63]
	s_waitcnt lgkmcnt(4)
	v_mfma_f32_32x32x16_bf16 v[48:63], v[212:215], v[140:143], v[48:63]
	s_waitcnt lgkmcnt(2)
	v_mfma_f32_32x32x16_bf16 v[48:63], v[216:219], v[152:155], v[48:63]
	s_waitcnt lgkmcnt(0)
	v_mfma_f32_32x32x16_bf16 v[48:63], v[220:223], v[160:163], v[48:63]
	s_barrier
	s_barrier
	s_branch .Lat_done

; __device__ __forceinline__ void expHalf(f32x16& p0) {
; #pragma unroll
;     for (int r = 0; r < 16; ++r) p0[r] = __builtin_amdgcn_exp2f(p0[r]);
; }
; __device__ __forceinline__ void finishSM(f32x16& p0, f32x16& p1, float& l_reg, bf16x8& pa0, bf16x8& pa1, bf16x8& pa2, bf16x8& pa3) {
;     float ps = 0;
; #pragma unroll
;     for (int r = 0; r < 16; ++r) ps += p0[r];
; #pragma unroll
;     for (int r = 0; r < 16; ++r) ps += p1[r];
;     l_reg += ps;
;     ...
;     PK4(p0, 0, pa0); PK4(p0, 8, pa1); PK4(p1, 0, pa2); PK4(p1, 8, pa3);
.Lat_far_g1l:
	s_mov_b32 m0, s33
	s_add_u32 s7, s33, 0x2000
	global_load_lds_dwordx4 v171, s[26:27]
	v_exp_f32_e32 v112, v112
	v_exp_f32_e32 v113, v113
	v_exp_f32_e32 v114, v114
	v_add_f32_e32 v64, v64, v112
	v_exp_f32_e32 v115, v115
	v_add_f32_e32 v65, v65, v113
	v_exp_f32_e32 v116, v116
	v_add_f32_e32 v66, v66, v114
	v_cvt_pk_bf16_f32 v208, v112, v113
	v_exp_f32_e32 v117, v117
	v_add_f32_e32 v67, v67, v115
	v_exp_f32_e32 v118, v118
	v_add_f32_e32 v64, v64, v116
	v_cvt_pk_bf16_f32 v209, v114, v115
	v_exp_f32_e32 v119, v119
	v_add_f32_e32 v65, v65, v117
	s_mov_b32 m0, s7
	s_xor_b32 s33, s33, 0x4000
	global_load_lds_dwordx4 v172, s[26:27]
	s_add_u32 s26, s26, 0x50000
	s_addc_u32 s27, s27, 0
	v_exp_f32_e32 v120, v120
	v_add_f32_e32 v66, v66, v118
	v_cvt_pk_bf16_f32 v210, v116, v117
	v_exp_f32_e32 v121, v121
	v_add_f32_e32 v67, v67, v119
	v_exp_f32_e32 v122, v122
	v_add_f32_e32 v64, v64, v120
	v_cvt_pk_bf16_f32 v211, v118, v119
	v_exp_f32_e32 v123, v123
	v_add_f32_e32 v65, v65, v121
	v_exp_f32_e32 v124, v124
	v_add_f32_e32 v66, v66, v122
	v_cvt_pk_bf16_f32 v212, v120, v121
	v_exp_f32_e32 v125, v125
	v_add_f32_e32 v67, v67, v123
	v_exp_f32_e32 v126, v126
	v_add_f32_e32 v64, v64, v124
	v_cvt_pk_bf16_f32 v213, v122, v123
	v_exp_f32_e32 v127, v127
	v_add_f32_e32 v65, v65, v125
	s_mov_b32 m0, s31
	s_add_u32 s7, s31, 0x2000
	global_load_lds_dwordx4 v169, s[24:25]
	v_exp_f32_e32 v192, v192
	v_add_f32_e32 v66, v66, v126
	v_cvt_pk_bf16_f32 v214, v124, v125
	v_exp_f32_e32 v193, v193
	v_add_f32_e32 v67, v67, v127
	v_cvt_pk_bf16_f32 v215, v126, v127
	v_exp_f32_e32 v194, v194
	v_add_f32_e32 v64, v64, v192
	v_exp_f32_e32 v195, v195
	v_add_f32_e32 v65, v65, v193
	v_cvt_pk_bf16_f32 v216, v192, v193
	v_exp_f32_e32 v196, v196
	v_add_f32_e32 v66, v66, v194
	v_exp_f32_e32 v197, v197
	v_add_f32_e32 v67, v67, v195
	v_cvt_pk_bf16_f32 v217, v194, v195
	s_mov_b32 m0, s7
	s_add_u32 s31, s31, s100
	global_load_lds_dwordx4 v170, s[24:25]
	s_add_u32 s24, s24, 0x50000
	s_addc_u32 s25, s25, 0
	v_exp_f32_e32 v198, v198
	v_add_f32_e32 v64, v64, v196
	v_exp_f32_e32 v199, v199
	v_add_f32_e32 v65, v65, v197
	v_cvt_pk_bf16_f32 v218, v196, v197
	v_exp_f32_e32 v200, v200
	v_add_f32_e32 v66, v66, v198
	v_exp_f32_e32 v201, v201
	v_add_f32_e32 v67, v67, v199
	v_cvt_pk_bf16_f32 v219, v198, v199
	v_exp_f32_e32 v202, v202
	v_add_f32_e32 v64, v64, v200
	v_exp_f32_e32 v203, v203
	v_add_f32_e32 v65, v65, v201
	v_cvt_pk_bf16_f32 v220, v200, v201
	v_exp_f32_e32 v204, v204
	v_add_f32_e32 v66, v66, v202
	v_exp_f32_e32 v205, v205
	v_add_f32_e32 v67, v67, v203
	v_cvt_pk_bf16_f32 v221, v202, v203
	v_exp_f32_e32 v206, v206
	v_add_f32_e32 v64, v64, v204
	v_exp_f32_e32 v207, v207
	v_add_f32_e32 v65, v65, v205
	v_cvt_pk_bf16_f32 v222, v204, v205
	v_add_f32_e32 v66, v66, v206
	v_add_f32_e32 v67, v67, v207
	v_cvt_pk_bf16_f32 v223, v206, v207
	s_add_i32 s99, s23, 64
	s_cmp_ge_i32 s99, s30
	s_cselect_b32 s6, s22, s98
	s_cmp_le_i32 s99, s29
	s_cselect_b32 s6, s21, s6
	s_nop 0
	s_cmp_lg_u32 s6, s9
	s_cbranch_scc0 .Lat_c0same_g1l
	s_mov_b32 s9, s6
	v_mov_b32_e32 v68, s9
	v_mov_b32_e32 v69, s9
	v_mov_b32_e32 v70, s9
	v_mov_b32_e32 v71, s9
	v_mov_b32_e32 v72, s9
	v_mov_b32_e32 v73, s9
	v_mov_b32_e32 v74, s9
	v_mov_b32_e32 v75, s9
	v_mov_b32_e32 v76, s9
	v_mov_b32_e32 v77, s9
	v_mov_b32_e32 v78, s9
	v_mov_b32_e32 v79, s9
	v_mov_b32_e32 v80, s9
	v_mov_b32_e32 v81, s9
	v_mov_b32_e32 v82, s9
	v_mov_b32_e32 v83, s9

; #define SBAR() __builtin_amdgcn_sched_barrier(0)
; #define PVLOAD(D0, X) do { X[0] = tr_read<v_rd_off(D0, 0, 0)>(vb); X[1] = tr_read<v_rd_off(D0, 0, 1)>(vb); X[2] = tr_read<v_rd_off(D0, 1, 0)>(vb); X[3] = tr_read<v_rd_off(D0, 1, 1)>(vb); \
;     X[4] = tr_read<v_rd_off(D0, 2, 0)>(vb); X[5] = tr_read<v_rd_off(D0, 2, 1)>(vb); X[6] = tr_read<v_rd_off(D0, 3, 0)>(vb); X[7] = tr_read<v_rd_off(D0, 3, 1)>(vb); } while (0)
; #define PVMMA(OD, X) do { OD = __builtin_amdgcn_mfma_f32_32x32x16_bf16(pa0, PVPK(X[0], X[1]), OD, 0, 0, 0); OD = __builtin_amdgcn_mfma_f32_32x32x16_bf16(pa1, PVPK(X[2], X[3]), OD, 0, 0, 0); \
;     OD = __builtin_amdgcn_mfma_f32_32x32x16_bf16(pa2, PVPK(X[4], X[5]), OD, 0, 0, 0); OD = __builtin_amdgcn_mfma_f32_32x32x16_bf16(pa3, PVPK(X[6], X[7]), OD, 0, 0, 0); } while (0)
; #define PVWAIT() do { asm volatile("s_waitcnt lgkmcnt(0)" ::: "memory"); SBAR(); } while (0)
; #define PVEXP(P, B, N) do { _Pragma("unroll") for (int r = (B); r < (B) + (N); ++r) P[r] = __builtin_amdgcn_exp2f(P[r]); } while (0)
; __device__ __forceinline__ void expHalf(f32x16& p0) {
; #pragma unroll
;     for (int r = 0; r < 16; ++r) p0[r] = __builtin_amdgcn_exp2f(p0[r]);
; }
; __device__ __forceinline__ void finishSM(f32x16& p0, f32x16& p1, float& l_reg, bf16x8& pa0, bf16x8& pa1, bf16x8& pa2, bf16x8& pa3) {
;     float ps = 0;
; #pragma unroll
;     for (int r = 0; r < 16; ++r) ps += p0[r];
; #pragma unroll
;     for (int r = 0; r < 16; ++r) ps += p1[r];
;     l_reg += ps;
;     ...
;     PK4(p0, 0, pa0); PK4(p0, 8, pa1); PK4(p1, 0, pa2); PK4(p1, 8, pa3);
; template <int NB> __device__ __forceinline__ void pv_blocks(f32x16* o, int vb, bf16x8 pa0, bf16x8 pa1, bf16x8 pa2, bf16x8 pa3, f32x16& pe0, f32x16& pe1) {
;     s16x4 x[8], y[8];
;     ...
;     PVLOAD(0, x); PVWAIT();
;     if (NB == 4) {
;         PVLOAD(1, y); SBAR(); PVMMA(o[0], x); PVEXP(pe0, 0, 8); SBAR(); PVWAIT();
;         PVLOAD(2, x); SBAR(); PVMMA(o[1], y); PVEXP(pe0, 8, 8); SBAR(); PVWAIT();
;         PVLOAD(3, y); SBAR(); PVMMA(o[2], x); PVEXP(pe1, 0, 8); SBAR(); PVWAIT();
;         PVMMA(o[3], y); PVEXP(pe1, 8, 8);
;     } else {
;         PVLOAD(1, y); SBAR(); PVMMA(o[0], x); PVEXP(pe0, 0, 16); SBAR(); PVWAIT();
;         PVMMA(o[1], y); PVEXP(pe1, 0, 16);
;     }
.Lat_far_g1p:
	v_exp_f32_e32 v112, v112
	v_exp_f32_e32 v113, v113
	v_exp_f32_e32 v114, v114
	v_add_f32_e32 v64, v64, v112
	v_exp_f32_e32 v115, v115
	v_add_f32_e32 v65, v65, v113
	v_exp_f32_e32 v116, v116
	v_add_f32_e32 v66, v66, v114
	v_cvt_pk_bf16_f32 v208, v112, v113
	v_exp_f32_e32 v117, v117
	v_add_f32_e32 v67, v67, v115
	v_exp_f32_e32 v118, v118
	v_add_f32_e32 v64, v64, v116
	v_cvt_pk_bf16_f32 v209, v114, v115
	v_exp_f32_e32 v119, v119
	v_add_f32_e32 v65, v65, v117
	v_exp_f32_e32 v120, v120
	v_add_f32_e32 v66, v66, v118
	v_cvt_pk_bf16_f32 v210, v116, v117
	v_exp_f32_e32 v121, v121
	v_add_f32_e32 v67, v67, v119
	v_exp_f32_e32 v122, v122
	v_add_f32_e32 v64, v64, v120
	v_cvt_pk_bf16_f32 v211, v118, v119
	v_exp_f32_e32 v123, v123
	v_add_f32_e32 v65, v65, v121
	v_exp_f32_e32 v124, v124
	v_add_f32_e32 v66, v66, v122
	v_cvt_pk_bf16_f32 v212, v120, v121
	v_exp_f32_e32 v125, v125
	v_add_f32_e32 v67, v67, v123
	v_exp_f32_e32 v126, v126
	v_add_f32_e32 v64, v64, v124
	v_cvt_pk_bf16_f32 v213, v122, v123
	v_exp_f32_e32 v127, v127
	v_add_f32_e32 v65, v65, v125
	v_exp_f32_e32 v192, v192
	v_add_f32_e32 v66, v66, v126
	v_cvt_pk_bf16_f32 v214, v124, v125
	v_exp_f32_e32 v193, v193
	v_add_f32_e32 v67, v67, v127
	v_cvt_pk_bf16_f32 v215, v126, v127
	v_exp_f32_e32 v194, v194
	v_add_f32_e32 v64, v64, v192
	v_exp_f32_e32 v195, v195
	v_add_f32_e32 v65, v65, v193
	v_cvt_pk_bf16_f32 v216, v192, v193
	v_exp_f32_e32 v196, v196
	v_add_f32_e32 v66, v66, v194
	v_exp_f32_e32 v197, v197
	v_add_f32_e32 v67, v67, v195
	v_cvt_pk_bf16_f32 v217, v194, v195
	v_exp_f32_e32 v198, v198
	v_add_f32_e32 v64, v64, v196
	v_exp_f32_e32 v199, v199
	v_add_f32_e32 v65, v65, v197
	v_cvt_pk_bf16_f32 v218, v196, v197
	v_exp_f32_e32 v200, v200
	v_add_f32_e32 v66, v66, v198
	v_exp_f32_e32 v201, v201
	v_add_f32_e32 v67, v67, v199
	v_cvt_pk_bf16_f32 v219, v198, v199
	v_exp_f32_e32 v202, v202
	v_add_f32_e32 v64, v64, v200
	v_exp_f32_e32 v203, v203
	v_add_f32_e32 v65, v65, v201
	v_cvt_pk_bf16_f32 v220, v200, v201
	v_exp_f32_e32 v204, v204
	v_add_f32_e32 v66, v66, v202
	v_exp_f32_e32 v205, v205
	v_add_f32_e32 v67, v67, v203
	v_cvt_pk_bf16_f32 v221, v202, v203
	v_exp_f32_e32 v206, v206
	v_add_f32_e32 v64, v64, v204
	v_exp_f32_e32 v207, v207
	v_add_f32_e32 v65, v65, v205
	v_cvt_pk_bf16_f32 v222, v204, v205
	v_add_f32_e32 v66, v66, v206
	v_add_f32_e32 v67, v67, v207
	v_cvt_pk_bf16_f32 v223, v206, v207
	s_nop 1
	s_waitcnt vmcnt(0)
	s_barrier
	s_setprio 0
	ds_read_b64_tr_b16 v[84:85], v168 offset:0
	ds_read_b64_tr_b16 v[86:87], v168 offset:2048
	ds_read_b64_tr_b16 v[88:89], v168 offset:4096
	ds_read_b64_tr_b16 v[90:91], v168 offset:6144
	ds_read_b64_tr_b16 v[92:93], v168 offset:8192
	ds_read_b64_tr_b16 v[94:95], v168 offset:10240
	ds_read_b64_tr_b16 v[128:129], v168 offset:12288
	ds_read_b64_tr_b16 v[130:131], v168 offset:14336
	ds_read_b64_tr_b16 v[132:133], v168 offset:512
	ds_read_b64_tr_b16 v[134:135], v168 offset:2560
	ds_read_b64_tr_b16 v[140:141], v168 offset:4608
	ds_read_b64_tr_b16 v[142:143], v168 offset:6656
	ds_read_b64_tr_b16 v[152:153], v168 offset:8704
	ds_read_b64_tr_b16 v[154:155], v168 offset:10752
	s_waitcnt lgkmcnt(12)
	v_mfma_f32_32x32x16_bf16 v[0:15], v[208:211], v[84:87], v[0:15]
	ds_read_b64_tr_b16 v[160:161], v168 offset:12800
	ds_read_b64_tr_b16 v[162:163], v168 offset:14848
	s_waitcnt lgkmcnt(12)
	v_mfma_f32_32x32x16_bf16 v[0:15], v[212:215], v[88:91], v[0:15]
	ds_read_b64_tr_b16 v[84:85], v168 offset:1024
	ds_read_b64_tr_b16 v[86:87], v168 offset:3072
	s_waitcnt lgkmcnt(12)
	v_mfma_f32_32x32x16_bf16 v[0:15], v[216:219], v[92:95], v[0:15]
	ds_read_b64_tr_b16 v[88:89], v168 offset:5120
	ds_read_b64_tr_b16 v[90:91], v168 offset:7168
	s_waitcnt lgkmcnt(12)
	v_mfma_f32_32x32x16_bf16 v[0:15], v[220:223], v[128:131], v[0:15]
	ds_read_b64_tr_b16 v[92:93], v168 offset:9216
	ds_read_b64_tr_b16 v[94:95], v168 offset:11264
	s_waitcnt lgkmcnt(12)
	v_mfma_f32_32x32x16_bf16 v[16:31], v[208:211], v[132:135], v[16:31]
	ds_read_b64_tr_b16 v[128:129], v168 offset:13312
	ds_read_b64_tr_b16 v[130:131], v168 offset:15360
	s_waitcnt lgkmcnt(12)
	v_mfma_f32_32x32x16_bf16 v[16:31], v[212:215], v[140:143], v[16:31]
	ds_read_b64_tr_b16 v[132:133], v168 offset:1536
	ds_read_b64_tr_b16 v[134:135], v168 offset:3584
	s_waitcnt lgkmcnt(12)
	v_mfma_f32_32x32x16_bf16 v[16:31], v[216:219], v[152:155], v[16:31]
	ds_read_b64_tr_b16 v[140:141], v168 offset:5632
	ds_read_b64_tr_b16 v[142:143], v168 offset:7680
	s_waitcnt lgkmcnt(12)
	v_mfma_f32_32x32x16_bf16 v[16:31], v[220:223], v[160:163], v[16:31]
	ds_read_b64_tr_b16 v[152:153], v168 offset:9728
	ds_read_b64_tr_b16 v[154:155], v168 offset:11776
	s_waitcnt lgkmcnt(12)
	v_mfma_f32_32x32x16_bf16 v[32:47], v[208:211], v[84:87], v[32:47]
	ds_read_b64_tr_b16 v[160:161], v168 offset:13824
	ds_read_b64_tr_b16 v[162:163], v168 offset:15872
	v_xor_b32_e32 v168, 0x4000, v168
	s_waitcnt lgkmcnt(12)
	v_mfma_f32_32x32x16_bf16 v[32:47], v[212:215], v[88:91], v[32:47]
	s_waitcnt lgkmcnt(10)
	v_mfma_f32_32x32x16_bf16 v[32:47], v[216:219], v[92:95], v[32:47]
	s_waitcnt lgkmcnt(8)
	v_mfma_f32_32x32x16_bf16 v[32:47], v[220:223], v[128:131], v[32:47]
	s_waitcnt lgkmcnt(6)
	v_mfma_f32_32x32x16_bf16 v[48:63], v[208:211], v[132:135], v[48:63]
	s_waitcnt lgkmcnt(4)
	v_mfma_f32_32x32x16_bf16 v[48:63], v[212:215], v[140:143], v[48:63]
	s_waitcnt lgkmcnt(2)
	v_mfma_f32_32x32x16_bf16 v[48:63], v[216:219], v[152:155], v[48:63]
	s_waitcnt lgkmcnt(0)
	v_mfma_f32_32x32x16_bf16 v[48:63], v[220:223], v[160:163], v[48:63]
	s_waitcnt vmcnt(0)
	s_barrier
